# v27 plus back-edge rotation in all 12 GEMM K-loops (exact)
# baseline (speedup 1.0000x reference)
.LBB0_486:
	s_or_b64 exec, exec, s[18:19]
	v_add_u32_e32 v179, s15, v3
	v_lshl_add_u64 v[6:7], s[16:17], 0, v[128:129]
	v_readfirstlane_b32 s16, v179
	v_lshl_add_u64 v[8:9], v[6:7], 0, s[22:23]
	s_mov_b32 m0, s16
	s_mov_b64 s[16:17], 0x18080
	v_add_u32_e32 v180, 0x2000, v179
	s_waitcnt vmcnt(0)
	s_barrier
	global_load_lds_dwordx4 v[8:9], off
	v_lshl_add_u64 v[8:9], v[6:7], 0, s[16:17]
	v_readfirstlane_b32 s16, v180
	v_mov_b32_e32 v131, v129
	v_add_u32_e32 v181, 0x8000, v165
	s_mov_b32 m0, s16
	v_lshl_add_u64 v[132:133], s[12:13], 0, v[130:131]
	v_readfirstlane_b32 s12, v181
	global_load_lds_dwordx4 v[8:9], off
	v_lshl_add_u64 v[8:9], v[132:133], 0, s[22:23]
	s_mov_b32 m0, s12
	s_mov_b64 s[12:13], 0x60080
	v_add_u32_e32 v184, 0xa000, v165
	global_load_lds_dwordx4 v[8:9], off
	v_lshl_add_u64 v[8:9], v[132:133], 0, s[12:13]
	v_readfirstlane_b32 s12, v184
	s_mov_b32 m0, s12
	s_mov_b64 s[12:13], 0x30080
	v_add_u32_e32 v185, s36, v3
	global_load_lds_dwordx4 v[8:9], off
	v_lshl_add_u64 v[8:9], v[6:7], 0, s[12:13]
	v_readfirstlane_b32 s12, v185
	s_mov_b32 m0, s12
	s_mov_b64 s[12:13], 0x48080
	v_add_u32_e32 v186, 0x2000, v185
	v_lshl_add_u64 v[6:7], v[6:7], 0, s[12:13]
	v_readfirstlane_b32 s12, v186
	global_load_lds_dwordx4 v[8:9], off
	s_mov_b32 m0, s12
	v_lshrrev_b32_e32 v16, 4, v2
	global_load_lds_dwordx4 v[6:7], off
	s_movk_i32 s16, 0x3000
	v_and_b32_e32 v167, 15, v170
	v_bfe_u32 v163, v170, 4, 2
	v_lshlrev_b32_e32 v171, 2, v170
	v_mul_lo_u32 v2, v16, s16
	v_bfe_u32 v5, v170, 2, 4
	v_lshlrev_b32_e32 v3, 4, v163
	v_lshlrev_b32_e32 v7, 6, v167
	v_and_b32_e32 v8, 32, v171
	v_lshlrev_b32_e32 v13, 6, v170
	v_or_b32_e32 v2, v1, v2
	s_movk_i32 s16, 0x300
	v_bitop3_b32 v7, v3, v8, v7 bitop3:0x36
	v_and_or_b32 v3, v13, s83, v3
	s_add_u32 s12, s72, s73
	v_mad_u32_u24 v2, v5, s16, v2
	v_xad_u32 v8, v3, v8, 16
	s_addc_u32 s13, s71, 0
	v_add_lshl_u32 v2, v2, v0, 1
	v_mov_b32_e32 v3, v129
	s_mov_b32 s16, 0xc000
	v_lshl_add_u64 v[134:135], s[12:13], 0, v[2:3]
	s_add_i32 s12, s26, s27
	v_mul_lo_u32 v2, v16, s16
	s_mul_hi_i32 s13, s12, 0x1800
	s_mulk_i32 s12, 0x1800
	v_or_b32_e32 v1, v1, v2
	s_movk_i32 s16, 0xc00
	v_ashrrev_i32_e32 v169, 6, v170
	s_add_u32 s12, s12, s70
	v_mad_u32_u24 v1, v5, s16, v1
	v_and_b32_e32 v168, 3, v169
	s_waitcnt vmcnt(6)
	v_lshlrev_b32_e32 v172, 6, v4
	v_lshlrev_b32_e32 v4, 13, v4
	s_addc_u32 s13, s13, 0
	v_add_lshl_u32 v0, v1, v0, 1
	v_mov_b32_e32 v1, v129
	v_lshlrev_b32_e32 v6, 12, v168
	v_add_u32_e32 v9, s35, v7
	v_add_u32_e32 v10, s14, v7
	v_add_u32_e32 v11, s15, v7
	v_add_u32_e32 v12, s36, v7
	v_add_u32_e32 v7, 16, v7
	v_or_b32_e32 v13, 0x800, v4
	v_or_b32_e32 v14, 0x1000, v4
	v_or_b32_e32 v15, 0x1800, v4
	v_lshl_add_u64 v[136:137], s[12:13], 0, v[0:1]
	v_mov_b32_e32 v0, 0
	s_mov_b32 s12, -2
	v_add_u32_e32 v188, v9, v6
	v_add_u32_e32 v176, v7, v4
	v_add_u32_e32 v175, v8, v13
	v_add_u32_e32 v174, v8, v14
	v_add_u32_e32 v173, v8, v15
	v_add_u32_e32 v187, v10, v6
	v_add_u32_e32 v178, v11, v6
	v_add_u32_e32 v177, v12, v6
	v_mov_b32_e32 v1, v0
	v_mov_b32_e32 v2, v0
	v_mov_b32_e32 v3, v0
	v_mov_b32_e32 v4, v0
	v_mov_b32_e32 v5, v0
	v_mov_b32_e32 v6, v0
	v_mov_b32_e32 v7, v0
	v_mov_b32_e32 v8, v0
	v_mov_b32_e32 v9, v0
	v_mov_b32_e32 v10, v0
	v_mov_b32_e32 v11, v0
	v_mov_b32_e32 v12, v0
	v_mov_b32_e32 v13, v0
	v_mov_b32_e32 v14, v0
	v_mov_b32_e32 v15, v0
	v_mov_b32_e32 v16, v0
	v_mov_b32_e32 v17, v0
	v_mov_b32_e32 v18, v0
	v_mov_b32_e32 v19, v0
	v_mov_b32_e32 v20, v0
	v_mov_b32_e32 v21, v0
	v_mov_b32_e32 v22, v0
	v_mov_b32_e32 v23, v0
	v_mov_b32_e32 v24, v0
	v_mov_b32_e32 v25, v0
	v_mov_b32_e32 v26, v0
	v_mov_b32_e32 v27, v0
	v_mov_b32_e32 v28, v0
	v_mov_b32_e32 v29, v0
	v_mov_b32_e32 v30, v0
	v_mov_b32_e32 v31, v0
	v_mov_b32_e32 v32, v0
	v_mov_b32_e32 v33, v0
	v_mov_b32_e32 v34, v0
	v_mov_b32_e32 v35, v0
	v_mov_b32_e32 v36, v0
	v_mov_b32_e32 v37, v0
	v_mov_b32_e32 v38, v0
	v_mov_b32_e32 v39, v0
	v_mov_b32_e32 v40, v0
	v_mov_b32_e32 v41, v0
	v_mov_b32_e32 v42, v0
	v_mov_b32_e32 v43, v0
	v_mov_b32_e32 v44, v0
	v_mov_b32_e32 v45, v0
	v_mov_b32_e32 v46, v0
	v_mov_b32_e32 v47, v0
	v_mov_b32_e32 v48, v0
	v_mov_b32_e32 v49, v0
	v_mov_b32_e32 v50, v0
	v_mov_b32_e32 v51, v0
	v_mov_b32_e32 v52, v0
	v_mov_b32_e32 v53, v0
	v_mov_b32_e32 v54, v0
	v_mov_b32_e32 v55, v0
	v_mov_b32_e32 v56, v0
	v_mov_b32_e32 v57, v0
	v_mov_b32_e32 v58, v0
	v_mov_b32_e32 v59, v0
	v_mov_b32_e32 v60, v0
	v_mov_b32_e32 v61, v0
	v_mov_b32_e32 v62, v0
	v_mov_b32_e32 v63, v0
	v_mov_b32_e32 v64, v0
	v_mov_b32_e32 v65, v0
	v_mov_b32_e32 v66, v0
	v_mov_b32_e32 v67, v0
	v_mov_b32_e32 v68, v0
	v_mov_b32_e32 v69, v0
	v_mov_b32_e32 v70, v0
	v_mov_b32_e32 v71, v0
	v_mov_b32_e32 v72, v0
	v_mov_b32_e32 v73, v0
	v_mov_b32_e32 v74, v0
	v_mov_b32_e32 v75, v0
	v_mov_b32_e32 v76, v0
	v_mov_b32_e32 v77, v0
	v_mov_b32_e32 v78, v0
	v_mov_b32_e32 v79, v0
	v_mov_b32_e32 v80, v0
	v_mov_b32_e32 v81, v0
	v_mov_b32_e32 v82, v0
	v_mov_b32_e32 v83, v0
	v_mov_b32_e32 v84, v0
	v_mov_b32_e32 v85, v0
	v_mov_b32_e32 v86, v0
	v_mov_b32_e32 v87, v0
	v_mov_b32_e32 v88, v0
	v_mov_b32_e32 v89, v0
	v_mov_b32_e32 v90, v0
	v_mov_b32_e32 v91, v0
	v_mov_b32_e32 v92, v0
	v_mov_b32_e32 v93, v0
	v_mov_b32_e32 v94, v0
	v_mov_b32_e32 v95, v0
	v_mov_b32_e32 v96, v0
	v_mov_b32_e32 v97, v0
	v_mov_b32_e32 v98, v0
	v_mov_b32_e32 v99, v0
	v_mov_b32_e32 v100, v0
	v_mov_b32_e32 v101, v0
	v_mov_b32_e32 v102, v0
	v_mov_b32_e32 v103, v0
	v_mov_b32_e32 v104, v0
	v_mov_b32_e32 v105, v0
	v_mov_b32_e32 v106, v0
	v_mov_b32_e32 v107, v0
	v_mov_b32_e32 v108, v0
	v_mov_b32_e32 v109, v0
	v_mov_b32_e32 v110, v0
	v_mov_b32_e32 v111, v0
	v_mov_b32_e32 v112, v0
	v_mov_b32_e32 v113, v0
	v_mov_b32_e32 v114, v0
	v_mov_b32_e32 v115, v0
	v_mov_b32_e32 v116, v0
	v_mov_b32_e32 v117, v0
	v_mov_b32_e32 v118, v0
	v_mov_b32_e32 v119, v0
	v_mov_b32_e32 v120, v0
	v_mov_b32_e32 v121, v0
	v_mov_b32_e32 v122, v0
	v_mov_b32_e32 v123, v0
	v_mov_b32_e32 v124, v0
	v_mov_b32_e32 v125, v0
	v_mov_b32_e32 v126, v0
	v_mov_b32_e32 v127, v0
.Lkh_487:
	s_barrier
.LBB0_487:
	ds_read_b128 v[138:141], v188
	ds_read_b128 v[146:149], v188 offset:1024
	ds_read_b128 v[150:153], v188 offset:2048
	ds_read_b128 v[154:157], v188 offset:3072
	v_add_u32_e32 v191, 0xc000, v165
	v_lshl_add_u64 v[242:243], s[10:11], 0, v[136:137]
	s_mov_b64 s[16:17], 0x96ec180
	v_readfirstlane_b32 s13, v191
	v_lshl_add_u64 v[192:193], v[242:243], 0, s[16:17]
	s_mov_b32 m0, s13
	ds_read_b128 v[194:197], v176
	ds_read_b128 v[198:201], v176 offset:1024
	ds_read_b128 v[202:205], v175
	ds_read_b128 v[206:209], v175 offset:1024
	ds_read_b128 v[210:213], v174
	ds_read_b128 v[214:217], v174 offset:1024
	ds_read_b128 v[218:221], v173
	ds_read_b128 v[222:225], v173 offset:1024
	global_load_lds_dwordx4 v[192:193], off
	v_add_u32_e32 v192, 0xe000, v165
	s_mov_b64 s[16:17], 0x974c180
	v_readfirstlane_b32 s13, v192
	v_lshl_add_u64 v[226:227], v[242:243], 0, s[16:17]
	s_mov_b32 m0, s13
	s_nop 0
	global_load_lds_dwordx4 v[226:227], off
	s_waitcnt lgkmcnt(8)
	s_barrier
	s_waitcnt lgkmcnt(0)
	s_setprio 1
	s_waitcnt lgkmcnt(0)
	v_mfma_f32_16x16x32_bf16 v[124:127], v[194:197], v[138:141], v[124:127]
	v_mfma_f32_16x16x32_bf16 v[120:123], v[194:197], v[150:153], v[120:123]
	v_mfma_f32_16x16x32_bf16 v[116:119], v[202:205], v[138:141], v[116:119]
	v_mfma_f32_16x16x32_bf16 v[112:115], v[202:205], v[150:153], v[112:115]
	v_mfma_f32_16x16x32_bf16 v[108:111], v[210:213], v[138:141], v[108:111]
	v_mfma_f32_16x16x32_bf16 v[104:107], v[210:213], v[150:153], v[104:107]
	v_mfma_f32_16x16x32_bf16 v[100:103], v[218:221], v[138:141], v[100:103]
	v_mfma_f32_16x16x32_bf16 v[96:99], v[218:221], v[150:153], v[96:99]
	v_mfma_f32_16x16x32_bf16 v[124:127], v[198:201], v[146:149], v[124:127]
	v_mfma_f32_16x16x32_bf16 v[120:123], v[198:201], v[154:157], v[120:123]
	v_mfma_f32_16x16x32_bf16 v[116:119], v[206:209], v[146:149], v[116:119]
	v_mfma_f32_16x16x32_bf16 v[112:115], v[206:209], v[154:157], v[112:115]
	v_mfma_f32_16x16x32_bf16 v[108:111], v[214:217], v[146:149], v[108:111]
	v_mfma_f32_16x16x32_bf16 v[104:107], v[214:217], v[154:157], v[104:107]
	v_mfma_f32_16x16x32_bf16 v[100:103], v[222:225], v[146:149], v[100:103]
	v_mfma_f32_16x16x32_bf16 v[96:99], v[222:225], v[154:157], v[96:99]
	s_setprio 0
	s_barrier
	v_lshl_add_u64 v[244:245], s[10:11], 0, v[134:135]
	s_mov_b64 s[16:17], 0x1362c200
	v_readfirstlane_b32 s13, v166
	v_add_u32_e32 v189, 0x2000, v166
	v_lshl_add_u64 v[246:247], v[244:245], 0, s[16:17]
	s_mov_b32 m0, s13
	s_mov_b64 s[16:17], 0x13644200
	v_readfirstlane_b32 s13, v189
	ds_read_b128 v[226:229], v187
	ds_read_b128 v[230:233], v187 offset:1024
	ds_read_b128 v[234:237], v187 offset:2048
	ds_read_b128 v[238:241], v187 offset:3072
	global_load_lds_dwordx4 v[246:247], off
	v_lshl_add_u64 v[246:247], v[244:245], 0, s[16:17]
	s_mov_b32 m0, s13
	s_nop 0
	global_load_lds_dwordx4 v[246:247], off
	s_barrier
	s_waitcnt lgkmcnt(0)
	s_setprio 1
	s_waitcnt lgkmcnt(0)
	v_mfma_f32_16x16x32_bf16 v[92:95], v[194:197], v[226:229], v[92:95]
	v_mfma_f32_16x16x32_bf16 v[88:91], v[194:197], v[234:237], v[88:91]
	v_mfma_f32_16x16x32_bf16 v[84:87], v[202:205], v[226:229], v[84:87]
	v_mfma_f32_16x16x32_bf16 v[80:83], v[202:205], v[234:237], v[80:83]
	v_mfma_f32_16x16x32_bf16 v[76:79], v[210:213], v[226:229], v[76:79]
	v_mfma_f32_16x16x32_bf16 v[72:75], v[210:213], v[234:237], v[72:75]
	v_mfma_f32_16x16x32_bf16 v[68:71], v[218:221], v[226:229], v[68:71]
	v_mfma_f32_16x16x32_bf16 v[64:67], v[218:221], v[234:237], v[64:67]
	v_mfma_f32_16x16x32_bf16 v[92:95], v[198:201], v[230:233], v[92:95]
	v_mfma_f32_16x16x32_bf16 v[88:91], v[198:201], v[238:241], v[88:91]
	v_mfma_f32_16x16x32_bf16 v[84:87], v[206:209], v[230:233], v[84:87]
	v_mfma_f32_16x16x32_bf16 v[80:83], v[206:209], v[238:241], v[80:83]
	v_mfma_f32_16x16x32_bf16 v[76:79], v[214:217], v[230:233], v[76:79]
	v_mfma_f32_16x16x32_bf16 v[72:75], v[214:217], v[238:241], v[72:75]
	v_mfma_f32_16x16x32_bf16 v[68:71], v[222:225], v[230:233], v[68:71]
	v_mfma_f32_16x16x32_bf16 v[64:67], v[222:225], v[238:241], v[64:67]
	s_setprio 0
	s_mov_b64 s[16:17], 0x962c200
	v_readfirstlane_b32 s13, v165
	v_lshl_add_u64 v[246:247], v[242:243], 0, s[16:17]
	s_mov_b32 m0, s13
	s_mov_b64 s[16:17], 0x968c200
	v_readfirstlane_b32 s13, v164
	s_barrier
	ds_read_b128 v[194:197], v176 offset:16384
	ds_read_b128 v[198:201], v176 offset:17408
	ds_read_b128 v[202:205], v175 offset:16384
	ds_read_b128 v[206:209], v175 offset:17408
	ds_read_b128 v[210:213], v174 offset:16384
	ds_read_b128 v[214:217], v174 offset:17408
	ds_read_b128 v[218:221], v173 offset:16384
	ds_read_b128 v[222:225], v173 offset:17408
	global_load_lds_dwordx4 v[246:247], off
	v_lshl_add_u64 v[246:247], v[242:243], 0, s[16:17]
	s_mov_b32 m0, s13
	s_nop 0
	global_load_lds_dwordx4 v[246:247], off
	s_barrier
	s_waitcnt lgkmcnt(0)
	s_setprio 1
	s_waitcnt lgkmcnt(0)
	v_mfma_f32_16x16x32_bf16 v[60:63], v[194:197], v[138:141], v[60:63]
	v_mfma_f32_16x16x32_bf16 v[56:59], v[194:197], v[150:153], v[56:59]
	v_mfma_f32_16x16x32_bf16 v[52:55], v[202:205], v[138:141], v[52:55]
	v_mfma_f32_16x16x32_bf16 v[48:51], v[202:205], v[150:153], v[48:51]
	v_mfma_f32_16x16x32_bf16 v[44:47], v[210:213], v[138:141], v[44:47]
	v_mfma_f32_16x16x32_bf16 v[40:43], v[210:213], v[150:153], v[40:43]
	v_mfma_f32_16x16x32_bf16 v[36:39], v[218:221], v[138:141], v[36:39]
	v_mfma_f32_16x16x32_bf16 v[32:35], v[218:221], v[150:153], v[32:35]
	v_mfma_f32_16x16x32_bf16 v[60:63], v[198:201], v[146:149], v[60:63]
	v_mfma_f32_16x16x32_bf16 v[56:59], v[198:201], v[154:157], v[56:59]
	v_mfma_f32_16x16x32_bf16 v[52:55], v[206:209], v[146:149], v[52:55]
	v_mfma_f32_16x16x32_bf16 v[48:51], v[206:209], v[154:157], v[48:51]
	v_mfma_f32_16x16x32_bf16 v[44:47], v[214:217], v[146:149], v[44:47]
	v_mfma_f32_16x16x32_bf16 v[40:43], v[214:217], v[154:157], v[40:43]
	v_mfma_f32_16x16x32_bf16 v[36:39], v[222:225], v[146:149], v[36:39]
	v_mfma_f32_16x16x32_bf16 v[32:35], v[222:225], v[154:157], v[32:35]
	s_setprio 0
	s_barrier
	s_mov_b64 s[16:17], 0x1365c200
	v_readfirstlane_b32 s13, v162
	v_add_u32_e32 v190, 0x2000, v162
	v_lshl_add_u64 v[138:139], v[244:245], 0, s[16:17]
	s_mov_b32 m0, s13
	s_mov_b64 s[16:17], 0x13674200
	v_readfirstlane_b32 s13, v190
	global_load_lds_dwordx4 v[138:139], off
	v_lshl_add_u64 v[138:139], v[244:245], 0, s[16:17]
	s_mov_b32 m0, s13
	s_nop 0
	global_load_lds_dwordx4 v[138:139], off
	s_waitcnt vmcnt(6)
	s_barrier
	s_setprio 1
	v_mfma_f32_16x16x32_bf16 v[28:31], v[194:197], v[226:229], v[28:31]
	v_mfma_f32_16x16x32_bf16 v[24:27], v[194:197], v[234:237], v[24:27]
	v_mfma_f32_16x16x32_bf16 v[20:23], v[202:205], v[226:229], v[20:23]
	v_mfma_f32_16x16x32_bf16 v[16:19], v[202:205], v[234:237], v[16:19]
	v_mfma_f32_16x16x32_bf16 v[12:15], v[210:213], v[226:229], v[12:15]
	v_mfma_f32_16x16x32_bf16 v[8:11], v[210:213], v[234:237], v[8:11]
	v_mfma_f32_16x16x32_bf16 v[4:7], v[218:221], v[226:229], v[4:7]
	v_mfma_f32_16x16x32_bf16 v[0:3], v[218:221], v[234:237], v[0:3]
	v_mfma_f32_16x16x32_bf16 v[28:31], v[198:201], v[230:233], v[28:31]
	v_mfma_f32_16x16x32_bf16 v[24:27], v[198:201], v[238:241], v[24:27]
	v_mfma_f32_16x16x32_bf16 v[20:23], v[206:209], v[230:233], v[20:23]
	v_mfma_f32_16x16x32_bf16 v[16:19], v[206:209], v[238:241], v[16:19]
	v_mfma_f32_16x16x32_bf16 v[12:15], v[214:217], v[230:233], v[12:15]
	v_mfma_f32_16x16x32_bf16 v[8:11], v[214:217], v[238:241], v[8:11]
	v_mfma_f32_16x16x32_bf16 v[4:7], v[222:225], v[230:233], v[4:7]
	v_mfma_f32_16x16x32_bf16 v[0:3], v[222:225], v[238:241], v[0:3]
	s_setprio 0
	s_barrier
	ds_read_b128 v[138:141], v178
	ds_read_b128 v[146:149], v178 offset:1024
	ds_read_b128 v[150:153], v178 offset:2048
	ds_read_b128 v[154:157], v178 offset:3072
	s_mov_b64 s[16:17], 0x96ec200
	v_readfirstlane_b32 s13, v161
	v_lshl_add_u64 v[226:227], v[242:243], 0, s[16:17]
	s_mov_b32 m0, s13
	s_mov_b64 s[16:17], 0x974c200
	v_readfirstlane_b32 s13, v160
	ds_read_b128 v[194:197], v176 offset:32768
	ds_read_b128 v[198:201], v176 offset:33792
	ds_read_b128 v[202:205], v175 offset:32768
	ds_read_b128 v[206:209], v175 offset:33792
	ds_read_b128 v[210:213], v174 offset:32768
	ds_read_b128 v[214:217], v174 offset:33792
	ds_read_b128 v[218:221], v173 offset:32768
	ds_read_b128 v[222:225], v173 offset:33792
	global_load_lds_dwordx4 v[226:227], off
	v_lshl_add_u64 v[226:227], v[242:243], 0, s[16:17]
	s_mov_b32 m0, s13
	s_nop 0
	global_load_lds_dwordx4 v[226:227], off
	s_waitcnt lgkmcnt(8)
	s_barrier
	s_waitcnt lgkmcnt(0)
	s_setprio 1
	s_waitcnt lgkmcnt(0)
	v_mfma_f32_16x16x32_bf16 v[124:127], v[194:197], v[138:141], v[124:127]
	v_mfma_f32_16x16x32_bf16 v[120:123], v[194:197], v[150:153], v[120:123]
	v_mfma_f32_16x16x32_bf16 v[116:119], v[202:205], v[138:141], v[116:119]
	v_mfma_f32_16x16x32_bf16 v[112:115], v[202:205], v[150:153], v[112:115]
	v_mfma_f32_16x16x32_bf16 v[108:111], v[210:213], v[138:141], v[108:111]
	v_mfma_f32_16x16x32_bf16 v[104:107], v[210:213], v[150:153], v[104:107]
	v_mfma_f32_16x16x32_bf16 v[100:103], v[218:221], v[138:141], v[100:103]
	v_mfma_f32_16x16x32_bf16 v[96:99], v[218:221], v[150:153], v[96:99]
	v_mfma_f32_16x16x32_bf16 v[124:127], v[198:201], v[146:149], v[124:127]
	v_mfma_f32_16x16x32_bf16 v[120:123], v[198:201], v[154:157], v[120:123]
	v_mfma_f32_16x16x32_bf16 v[116:119], v[206:209], v[146:149], v[116:119]
	v_mfma_f32_16x16x32_bf16 v[112:115], v[206:209], v[154:157], v[112:115]
	v_mfma_f32_16x16x32_bf16 v[108:111], v[214:217], v[146:149], v[108:111]
	v_mfma_f32_16x16x32_bf16 v[104:107], v[214:217], v[154:157], v[104:107]
	v_mfma_f32_16x16x32_bf16 v[100:103], v[222:225], v[146:149], v[100:103]
	v_mfma_f32_16x16x32_bf16 v[96:99], v[222:225], v[154:157], v[96:99]
	s_setprio 0
	s_barrier
	s_mov_b64 s[16:17], 0x1362c280
	v_readfirstlane_b32 s13, v179
	v_lshl_add_u64 v[246:247], v[244:245], 0, s[16:17]
	s_mov_b32 m0, s13
	s_mov_b64 s[16:17], 0x13644280
	v_readfirstlane_b32 s13, v180
	ds_read_b128 v[226:229], v177
	ds_read_b128 v[230:233], v177 offset:1024
	ds_read_b128 v[234:237], v177 offset:2048
	ds_read_b128 v[238:241], v177 offset:3072
	global_load_lds_dwordx4 v[246:247], off
	v_lshl_add_u64 v[246:247], v[244:245], 0, s[16:17]
	s_mov_b32 m0, s13
	s_nop 0
	global_load_lds_dwordx4 v[246:247], off
	s_barrier
	s_waitcnt lgkmcnt(0)
	s_setprio 1
	s_waitcnt lgkmcnt(0)
	v_mfma_f32_16x16x32_bf16 v[92:95], v[194:197], v[226:229], v[92:95]
	v_mfma_f32_16x16x32_bf16 v[88:91], v[194:197], v[234:237], v[88:91]
	v_mfma_f32_16x16x32_bf16 v[84:87], v[202:205], v[226:229], v[84:87]
	v_mfma_f32_16x16x32_bf16 v[80:83], v[202:205], v[234:237], v[80:83]
	v_mfma_f32_16x16x32_bf16 v[76:79], v[210:213], v[226:229], v[76:79]
	v_mfma_f32_16x16x32_bf16 v[72:75], v[210:213], v[234:237], v[72:75]
	v_mfma_f32_16x16x32_bf16 v[68:71], v[218:221], v[226:229], v[68:71]
	v_mfma_f32_16x16x32_bf16 v[64:67], v[218:221], v[234:237], v[64:67]
	v_mfma_f32_16x16x32_bf16 v[92:95], v[198:201], v[230:233], v[92:95]
	v_mfma_f32_16x16x32_bf16 v[88:91], v[198:201], v[238:241], v[88:91]
	v_mfma_f32_16x16x32_bf16 v[84:87], v[206:209], v[230:233], v[84:87]
	v_mfma_f32_16x16x32_bf16 v[80:83], v[206:209], v[238:241], v[80:83]
	v_mfma_f32_16x16x32_bf16 v[76:79], v[214:217], v[230:233], v[76:79]
	v_mfma_f32_16x16x32_bf16 v[72:75], v[214:217], v[238:241], v[72:75]
	v_mfma_f32_16x16x32_bf16 v[68:71], v[222:225], v[230:233], v[68:71]
	v_mfma_f32_16x16x32_bf16 v[64:67], v[222:225], v[238:241], v[64:67]
	s_setprio 0
	s_mov_b64 s[16:17], 0x962c280
	v_readfirstlane_b32 s13, v181
	v_lshl_add_u64 v[246:247], v[242:243], 0, s[16:17]
	s_mov_b32 m0, s13
	s_mov_b64 s[16:17], 0x968c280
	v_readfirstlane_b32 s13, v184
	s_barrier
	ds_read_b128 v[194:197], v176 offset:49152
	ds_read_b128 v[198:201], v176 offset:50176
	ds_read_b128 v[202:205], v175 offset:49152
	ds_read_b128 v[206:209], v175 offset:50176
	ds_read_b128 v[210:213], v174 offset:49152
	ds_read_b128 v[214:217], v174 offset:50176
	ds_read_b128 v[218:221], v173 offset:49152
	ds_read_b128 v[222:225], v173 offset:50176
	global_load_lds_dwordx4 v[246:247], off
	v_lshl_add_u64 v[242:243], v[242:243], 0, s[16:17]
	s_mov_b32 m0, s13
	s_nop 0
	global_load_lds_dwordx4 v[242:243], off
	s_barrier
	s_waitcnt lgkmcnt(0)
	s_setprio 1
	s_waitcnt lgkmcnt(0)
	v_mfma_f32_16x16x32_bf16 v[60:63], v[194:197], v[138:141], v[60:63]
	v_mfma_f32_16x16x32_bf16 v[56:59], v[194:197], v[150:153], v[56:59]
	v_mfma_f32_16x16x32_bf16 v[52:55], v[202:205], v[138:141], v[52:55]
	v_mfma_f32_16x16x32_bf16 v[48:51], v[202:205], v[150:153], v[48:51]
	v_mfma_f32_16x16x32_bf16 v[44:47], v[210:213], v[138:141], v[44:47]
	v_mfma_f32_16x16x32_bf16 v[40:43], v[210:213], v[150:153], v[40:43]
	v_mfma_f32_16x16x32_bf16 v[36:39], v[218:221], v[138:141], v[36:39]
	v_mfma_f32_16x16x32_bf16 v[32:35], v[218:221], v[150:153], v[32:35]
	v_mfma_f32_16x16x32_bf16 v[60:63], v[198:201], v[146:149], v[60:63]
	v_mfma_f32_16x16x32_bf16 v[56:59], v[198:201], v[154:157], v[56:59]
	v_mfma_f32_16x16x32_bf16 v[52:55], v[206:209], v[146:149], v[52:55]
	v_mfma_f32_16x16x32_bf16 v[48:51], v[206:209], v[154:157], v[48:51]
	v_mfma_f32_16x16x32_bf16 v[44:47], v[214:217], v[146:149], v[44:47]
	v_mfma_f32_16x16x32_bf16 v[40:43], v[214:217], v[154:157], v[40:43]
	v_mfma_f32_16x16x32_bf16 v[36:39], v[222:225], v[146:149], v[36:39]
	v_mfma_f32_16x16x32_bf16 v[32:35], v[222:225], v[154:157], v[32:35]
	s_setprio 0
	s_barrier
	s_mov_b64 s[16:17], 0x1365c280
	v_readfirstlane_b32 s13, v185
	v_lshl_add_u64 v[138:139], v[244:245], 0, s[16:17]
	s_mov_b32 m0, s13
	s_mov_b64 s[16:17], 0x13674280
	v_readfirstlane_b32 s13, v186
	global_load_lds_dwordx4 v[138:139], off
	v_lshl_add_u64 v[138:139], v[244:245], 0, s[16:17]
	s_mov_b32 m0, s13
	s_nop 0
	global_load_lds_dwordx4 v[138:139], off
	s_waitcnt vmcnt(6)
	s_barrier
	s_setprio 1
	v_mfma_f32_16x16x32_bf16 v[28:31], v[194:197], v[226:229], v[28:31]
	v_mfma_f32_16x16x32_bf16 v[24:27], v[194:197], v[234:237], v[24:27]
	v_mfma_f32_16x16x32_bf16 v[20:23], v[202:205], v[226:229], v[20:23]
	v_mfma_f32_16x16x32_bf16 v[16:19], v[202:205], v[234:237], v[16:19]
	v_mfma_f32_16x16x32_bf16 v[12:15], v[210:213], v[226:229], v[12:15]
	v_mfma_f32_16x16x32_bf16 v[8:11], v[210:213], v[234:237], v[8:11]
	v_mfma_f32_16x16x32_bf16 v[4:7], v[218:221], v[226:229], v[4:7]
	v_mfma_f32_16x16x32_bf16 v[0:3], v[218:221], v[234:237], v[0:3]
	v_mfma_f32_16x16x32_bf16 v[28:31], v[198:201], v[230:233], v[28:31]
	v_mfma_f32_16x16x32_bf16 v[24:27], v[198:201], v[238:241], v[24:27]
	v_mfma_f32_16x16x32_bf16 v[20:23], v[206:209], v[230:233], v[20:23]
	v_mfma_f32_16x16x32_bf16 v[16:19], v[206:209], v[238:241], v[16:19]
	v_mfma_f32_16x16x32_bf16 v[12:15], v[214:217], v[230:233], v[12:15]
	v_mfma_f32_16x16x32_bf16 v[8:11], v[214:217], v[238:241], v[8:11]
	v_mfma_f32_16x16x32_bf16 v[4:7], v[222:225], v[230:233], v[4:7]
	v_mfma_f32_16x16x32_bf16 v[0:3], v[222:225], v[238:241], v[0:3]
	s_setprio 0
	s_add_i32 s12, s12, 2
	v_lshl_add_u64 v[134:135], v[134:135], 0, s[40:41]
	s_cmp_lt_u32 s12, 8
	v_lshl_add_u64 v[136:137], v[136:137], 0, s[40:41]
	s_cbranch_scc1 .Lkh_487
	s_barrier
	s_mov_b64 s[12:13], 0xc0580
	v_lshl_add_u64 v[180:181], v[132:133], 0, s[12:13]
	v_readfirstlane_b32 s12, v191
	s_mov_b32 m0, s12
	s_mov_b64 s[12:13], 0x120580
	v_lshl_add_u64 v[132:133], v[132:133], 0, s[12:13]
	v_readfirstlane_b32 s12, v192
	ds_read_b128 v[134:137], v188
	ds_read_b128 v[138:141], v188 offset:1024
	ds_read_b128 v[146:149], v188 offset:2048
	ds_read_b128 v[150:153], v188 offset:3072
	ds_read_b128 v[154:157], v176
	ds_read_b128 v[194:197], v176 offset:1024
	ds_read_b128 v[198:201], v175
	ds_read_b128 v[202:205], v175 offset:1024
	ds_read_b128 v[206:209], v174
	ds_read_b128 v[210:213], v174 offset:1024
	ds_read_b128 v[214:217], v173
	ds_read_b128 v[218:221], v173 offset:1024
	global_load_lds_dwordx4 v[180:181], off
	s_mov_b32 m0, s12
	s_nop 0
	global_load_lds_dwordx4 v[132:133], off
	s_barrier
	s_waitcnt lgkmcnt(0)
	s_setprio 1
	s_waitcnt lgkmcnt(0)
	v_mfma_f32_16x16x32_bf16 v[124:127], v[154:157], v[134:137], v[124:127]
	v_mfma_f32_16x16x32_bf16 v[120:123], v[154:157], v[146:149], v[120:123]
	v_mfma_f32_16x16x32_bf16 v[116:119], v[198:201], v[134:137], v[116:119]
	v_mfma_f32_16x16x32_bf16 v[112:115], v[198:201], v[146:149], v[112:115]
	v_mfma_f32_16x16x32_bf16 v[124:127], v[194:197], v[138:141], v[124:127]
	v_mfma_f32_16x16x32_bf16 v[120:123], v[194:197], v[150:153], v[120:123]
	v_mfma_f32_16x16x32_bf16 v[116:119], v[202:205], v[138:141], v[116:119]
	v_mfma_f32_16x16x32_bf16 v[112:115], v[202:205], v[150:153], v[112:115]
	v_mfma_f32_16x16x32_bf16 v[108:111], v[206:209], v[134:137], v[108:111]
	v_mfma_f32_16x16x32_bf16 v[104:107], v[206:209], v[146:149], v[104:107]
	v_mfma_f32_16x16x32_bf16 v[100:103], v[214:217], v[134:137], v[100:103]
	v_mfma_f32_16x16x32_bf16 v[96:99], v[214:217], v[146:149], v[96:99]
	v_mfma_f32_16x16x32_bf16 v[222:225], v[210:213], v[138:141], v[108:111]
	v_mfma_f32_16x16x32_bf16 v[226:229], v[210:213], v[150:153], v[104:107]
	v_mfma_f32_16x16x32_bf16 v[230:233], v[218:221], v[138:141], v[100:103]
	v_mfma_f32_16x16x32_bf16 v[234:237], v[218:221], v[150:153], v[96:99]
	s_setprio 0
	s_barrier
	s_nop 1
	ds_read_b128 v[96:99], v187
	ds_read_b128 v[100:103], v187 offset:1024
	ds_read_b128 v[104:107], v187 offset:2048
	ds_read_b128 v[108:111], v187 offset:3072
	s_barrier
	s_waitcnt lgkmcnt(0)
	s_setprio 1
	s_waitcnt lgkmcnt(0)
	v_mfma_f32_16x16x32_bf16 v[92:95], v[154:157], v[96:99], v[92:95]
	v_mfma_f32_16x16x32_bf16 v[88:91], v[154:157], v[104:107], v[88:91]
	v_mfma_f32_16x16x32_bf16 v[84:87], v[198:201], v[96:99], v[84:87]
	v_mfma_f32_16x16x32_bf16 v[80:83], v[198:201], v[104:107], v[80:83]
	v_mfma_f32_16x16x32_bf16 v[92:95], v[194:197], v[100:103], v[92:95]
	v_mfma_f32_16x16x32_bf16 v[88:91], v[194:197], v[108:111], v[88:91]
	v_mfma_f32_16x16x32_bf16 v[84:87], v[202:205], v[100:103], v[84:87]
	v_mfma_f32_16x16x32_bf16 v[80:83], v[202:205], v[108:111], v[80:83]
	v_mfma_f32_16x16x32_bf16 v[76:79], v[206:209], v[96:99], v[76:79]
	v_mfma_f32_16x16x32_bf16 v[72:75], v[206:209], v[104:107], v[72:75]
	v_mfma_f32_16x16x32_bf16 v[68:71], v[214:217], v[96:99], v[68:71]
	v_mfma_f32_16x16x32_bf16 v[64:67], v[214:217], v[104:107], v[64:67]
	v_mfma_f32_16x16x32_bf16 v[154:157], v[210:213], v[100:103], v[76:79]
	v_mfma_f32_16x16x32_bf16 v[184:187], v[210:213], v[108:111], v[72:75]
	v_mfma_f32_16x16x32_bf16 v[192:195], v[218:221], v[100:103], v[68:71]
	v_mfma_f32_16x16x32_bf16 v[196:199], v[218:221], v[108:111], v[64:67]
	s_setprio 0
	s_barrier
	s_nop 1
	ds_read_b128 v[64:67], v176 offset:16384
	ds_read_b128 v[68:71], v176 offset:17408
	ds_read_b128 v[72:75], v175 offset:16384
	ds_read_b128 v[76:79], v175 offset:17408
	ds_read_b128 v[200:203], v174 offset:16384
	ds_read_b128 v[204:207], v174 offset:17408
	ds_read_b128 v[208:211], v173 offset:16384
	ds_read_b128 v[212:215], v173 offset:17408
	s_waitcnt vmcnt(4)
	s_barrier
	s_waitcnt lgkmcnt(0)
	s_setprio 1
	s_waitcnt lgkmcnt(0)
	v_mfma_f32_16x16x32_bf16 v[60:63], v[64:67], v[134:137], v[60:63]
	v_mfma_f32_16x16x32_bf16 v[56:59], v[64:67], v[146:149], v[56:59]
	v_mfma_f32_16x16x32_bf16 v[52:55], v[72:75], v[134:137], v[52:55]
	v_mfma_f32_16x16x32_bf16 v[48:51], v[72:75], v[146:149], v[48:51]
	v_mfma_f32_16x16x32_bf16 v[60:63], v[68:71], v[138:141], v[60:63]
	v_mfma_f32_16x16x32_bf16 v[56:59], v[68:71], v[150:153], v[56:59]
	v_mfma_f32_16x16x32_bf16 v[52:55], v[76:79], v[138:141], v[52:55]
	v_mfma_f32_16x16x32_bf16 v[48:51], v[76:79], v[150:153], v[48:51]
	v_mfma_f32_16x16x32_bf16 v[44:47], v[200:203], v[134:137], v[44:47]
	v_mfma_f32_16x16x32_bf16 v[40:43], v[200:203], v[146:149], v[40:43]
	v_mfma_f32_16x16x32_bf16 v[36:39], v[208:211], v[134:137], v[36:39]
	v_mfma_f32_16x16x32_bf16 v[32:35], v[208:211], v[146:149], v[32:35]
	v_mfma_f32_16x16x32_bf16 v[216:219], v[204:207], v[138:141], v[44:47]
	v_mfma_f32_16x16x32_bf16 v[238:241], v[204:207], v[150:153], v[40:43]
	v_mfma_f32_16x16x32_bf16 v[132:135], v[212:215], v[138:141], v[36:39]
	v_mfma_f32_16x16x32_bf16 v[136:139], v[212:215], v[150:153], v[32:35]
	s_setprio 0
	s_setprio 1
	v_mfma_f32_16x16x32_bf16 v[28:31], v[64:67], v[96:99], v[28:31]
	v_mfma_f32_16x16x32_bf16 v[24:27], v[64:67], v[104:107], v[24:27]
	v_mfma_f32_16x16x32_bf16 v[20:23], v[72:75], v[96:99], v[20:23]
	v_mfma_f32_16x16x32_bf16 v[16:19], v[72:75], v[104:107], v[16:19]
	v_mfma_f32_16x16x32_bf16 v[28:31], v[68:71], v[100:103], v[28:31]
	v_mfma_f32_16x16x32_bf16 v[24:27], v[68:71], v[108:111], v[24:27]
	v_mfma_f32_16x16x32_bf16 v[20:23], v[76:79], v[100:103], v[20:23]
	v_mfma_f32_16x16x32_bf16 v[16:19], v[76:79], v[108:111], v[16:19]
	v_mfma_f32_16x16x32_bf16 v[12:15], v[200:203], v[96:99], v[12:15]
	v_mfma_f32_16x16x32_bf16 v[8:11], v[200:203], v[104:107], v[8:11]
	v_mfma_f32_16x16x32_bf16 v[4:7], v[208:211], v[96:99], v[4:7]
	v_mfma_f32_16x16x32_bf16 v[0:3], v[208:211], v[104:107], v[0:3]
	v_mfma_f32_16x16x32_bf16 v[146:149], v[204:207], v[100:103], v[12:15]
	v_mfma_f32_16x16x32_bf16 v[150:153], v[204:207], v[108:111], v[8:11]
	v_mfma_f32_16x16x32_bf16 v[200:203], v[212:215], v[100:103], v[4:7]
	v_mfma_f32_16x16x32_bf16 v[204:207], v[212:215], v[108:111], v[0:3]
	s_setprio 0
	s_barrier
	s_nop 1
	ds_read_b128 v[0:3], v178
	ds_read_b128 v[4:7], v178 offset:1024
	ds_read_b128 v[208:211], v178 offset:2048
	ds_read_b128 v[178:181], v178 offset:3072
	ds_read_b128 v[8:11], v176 offset:32768
	ds_read_b128 v[12:15], v176 offset:33792
	ds_read_b128 v[32:35], v175 offset:32768
	ds_read_b128 v[36:39], v175 offset:33792
	ds_read_b128 v[40:43], v174 offset:32768
	ds_read_b128 v[44:47], v174 offset:33792
	ds_read_b128 v[212:215], v173 offset:32768
	ds_read_b128 v[242:245], v173 offset:33792
	s_waitcnt vmcnt(2)
	s_barrier
	s_waitcnt lgkmcnt(0)
	s_setprio 1
	s_waitcnt lgkmcnt(0)
	v_mfma_f32_16x16x32_bf16 v[64:67], v[8:11], v[0:3], v[124:127]
	v_mfma_f32_16x16x32_bf16 v[104:107], v[12:15], v[4:7], v[64:67]
	v_mfma_f32_16x16x32_bf16 v[64:67], v[8:11], v[208:211], v[120:123]
	v_mfma_f32_16x16x32_bf16 v[108:111], v[12:15], v[178:181], v[64:67]
	v_mfma_f32_16x16x32_bf16 v[64:67], v[32:35], v[0:3], v[116:119]
	v_mfma_f32_16x16x32_bf16 v[96:99], v[36:39], v[4:7], v[64:67]
	v_mfma_f32_16x16x32_bf16 v[64:67], v[32:35], v[208:211], v[112:115]
	v_mfma_f32_16x16x32_bf16 v[100:103], v[36:39], v[178:181], v[64:67]
	v_mfma_f32_16x16x32_bf16 v[64:67], v[40:43], v[0:3], v[222:225]
	v_mfma_f32_16x16x32_bf16 v[72:75], v[44:47], v[4:7], v[64:67]
	v_mfma_f32_16x16x32_bf16 v[64:67], v[40:43], v[208:211], v[226:229]
	v_mfma_f32_16x16x32_bf16 v[76:79], v[44:47], v[178:181], v[64:67]
	v_mfma_f32_16x16x32_bf16 v[64:67], v[212:215], v[0:3], v[230:233]
	v_mfma_f32_16x16x32_bf16 v[68:71], v[212:215], v[208:211], v[234:237]
	v_mfma_f32_16x16x32_bf16 v[64:67], v[242:245], v[4:7], v[64:67]
	v_mfma_f32_16x16x32_bf16 v[68:71], v[242:245], v[178:181], v[68:71]
	s_setprio 0
	s_barrier
	ds_read_b128 v[220:223], v177
	ds_read_b128 v[224:227], v177 offset:1024
	ds_read_b128 v[228:231], v177 offset:2048
	ds_read_b128 v[232:235], v177 offset:3072
	s_waitcnt vmcnt(0)
	s_barrier
	s_waitcnt lgkmcnt(0)
	s_setprio 1
	s_waitcnt lgkmcnt(0)
	v_mfma_f32_16x16x32_bf16 v[92:95], v[8:11], v[220:223], v[92:95]
	v_mfma_f32_16x16x32_bf16 v[8:11], v[8:11], v[228:231], v[88:91]
	v_mfma_f32_16x16x32_bf16 v[124:127], v[12:15], v[232:235], v[8:11]
	v_mfma_f32_16x16x32_bf16 v[8:11], v[32:35], v[220:223], v[84:87]
	v_mfma_f32_16x16x32_bf16 v[112:115], v[36:39], v[224:227], v[8:11]
	v_mfma_f32_16x16x32_bf16 v[8:11], v[32:35], v[228:231], v[80:83]
	v_mfma_f32_16x16x32_bf16 v[116:119], v[36:39], v[232:235], v[8:11]
	v_mfma_f32_16x16x32_bf16 v[8:11], v[40:43], v[220:223], v[154:157]
	v_mfma_f32_16x16x32_bf16 v[88:91], v[44:47], v[224:227], v[8:11]
	v_mfma_f32_16x16x32_bf16 v[8:11], v[40:43], v[228:231], v[184:187]
	v_mfma_f32_16x16x32_bf16 v[120:123], v[12:15], v[224:227], v[92:95]
	v_mfma_f32_16x16x32_bf16 v[92:95], v[44:47], v[232:235], v[8:11]
	v_mfma_f32_16x16x32_bf16 v[8:11], v[212:215], v[220:223], v[192:195]
	v_mfma_f32_16x16x32_bf16 v[80:83], v[242:245], v[224:227], v[8:11]
	v_mfma_f32_16x16x32_bf16 v[8:11], v[212:215], v[228:231], v[196:199]
	v_mfma_f32_16x16x32_bf16 v[84:87], v[242:245], v[232:235], v[8:11]
	s_setprio 0
	s_barrier
	ds_read_b128 v[154:157], v176 offset:49152
	ds_read_b128 v[184:187], v176 offset:50176
	ds_read_b128 v[192:195], v175 offset:49152
	ds_read_b128 v[196:199], v175 offset:50176
	ds_read_b128 v[212:215], v174 offset:49152
	ds_read_b128 v[174:177], v174 offset:50176
	ds_read_b128 v[242:245], v173 offset:49152
	ds_read_b128 v[246:249], v173 offset:50176
	s_barrier
	s_waitcnt lgkmcnt(0)
	s_setprio 1
	s_waitcnt lgkmcnt(0)
	v_mfma_f32_16x16x32_bf16 v[8:11], v[154:157], v[0:3], v[60:63]
	v_mfma_f32_16x16x32_bf16 v[40:43], v[184:187], v[4:7], v[8:11]
	v_mfma_f32_16x16x32_bf16 v[8:11], v[154:157], v[208:211], v[56:59]
	v_mfma_f32_16x16x32_bf16 v[44:47], v[184:187], v[178:181], v[8:11]
	v_mfma_f32_16x16x32_bf16 v[8:11], v[192:195], v[0:3], v[52:55]
	v_mfma_f32_16x16x32_bf16 v[32:35], v[196:199], v[4:7], v[8:11]
	v_mfma_f32_16x16x32_bf16 v[8:11], v[192:195], v[208:211], v[48:51]
	v_mfma_f32_16x16x32_bf16 v[36:39], v[196:199], v[178:181], v[8:11]
	v_mfma_f32_16x16x32_bf16 v[8:11], v[212:215], v[0:3], v[216:219]
	v_mfma_f32_16x16x32_bf16 v[0:3], v[242:245], v[0:3], v[132:135]
	v_mfma_f32_16x16x32_bf16 v[8:11], v[174:177], v[4:7], v[8:11]
	v_mfma_f32_16x16x32_bf16 v[12:15], v[212:215], v[208:211], v[238:241]
	v_mfma_f32_16x16x32_bf16 v[0:3], v[246:249], v[4:7], v[0:3]
	v_mfma_f32_16x16x32_bf16 v[4:7], v[242:245], v[208:211], v[136:139]
	v_mfma_f32_16x16x32_bf16 v[12:15], v[174:177], v[178:181], v[12:15]
	v_mfma_f32_16x16x32_bf16 v[4:7], v[246:249], v[178:181], v[4:7]
	s_setprio 0
	s_setprio 1
	v_mfma_f32_16x16x32_bf16 v[16:19], v[192:195], v[228:231], v[16:19]
	v_mfma_f32_16x16x32_bf16 v[24:27], v[154:157], v[228:231], v[24:27]
	v_mfma_f32_16x16x32_bf16 v[52:55], v[196:199], v[232:235], v[16:19]
	v_mfma_f32_16x16x32_bf16 v[16:19], v[212:215], v[220:223], v[146:149]
	v_mfma_f32_16x16x32_bf16 v[28:31], v[154:157], v[220:223], v[28:31]
	v_mfma_f32_16x16x32_bf16 v[60:63], v[184:187], v[232:235], v[24:27]
	v_mfma_f32_16x16x32_bf16 v[20:23], v[192:195], v[220:223], v[20:23]
	v_mfma_f32_16x16x32_bf16 v[24:27], v[174:177], v[224:227], v[16:19]
	v_mfma_f32_16x16x32_bf16 v[16:19], v[212:215], v[228:231], v[150:153]
	v_mfma_f32_16x16x32_bf16 v[56:59], v[184:187], v[224:227], v[28:31]
	v_mfma_f32_16x16x32_bf16 v[48:51], v[196:199], v[224:227], v[20:23]
	v_mfma_f32_16x16x32_bf16 v[28:31], v[174:177], v[232:235], v[16:19]
	v_mfma_f32_16x16x32_bf16 v[16:19], v[242:245], v[220:223], v[200:203]
	v_mfma_f32_16x16x32_bf16 v[20:23], v[242:245], v[228:231], v[204:207]
	v_mfma_f32_16x16x32_bf16 v[16:19], v[246:249], v[224:227], v[16:19]
	v_mfma_f32_16x16x32_bf16 v[20:23], v[246:249], v[232:235], v[20:23]
	s_setprio 0
	v_cmp_gt_u32_e32 vcc, s92, v170
	s_barrier
	s_and_saveexec_b64 s[12:13], vcc
	s_cbranch_execz .LBB0_490
	s_barrier
